# sparse attention phase: the static s_setprio 1 on waves 0-3 instead of 4-7
# baseline (speedup 1.0000x reference)
.LBB0_2063:
	s_or_b64 exec, exec, s[0:1]
	s_cmpk_gt_i32 s90, 0x3ff
	v_readlane_b32 s68, v251, 50
	v_readlane_b32 s69, v251, 51
	s_waitcnt lgkmcnt(0)
	s_barrier
	s_cbranch_scc1 .LBB0_2167
	v_readlane_b32 s0, v251, 7
	v_and_b32_e32 v112, 15, v152
	v_lshrrev_b32_e32 v113, 4, v152
	s_nop 1
	s_and_b32 s34, s0, 3
	s_lshr_b32 s35, s0, 2
	v_lshrrev_b32_e32 v220, 3, v153
	v_and_b32_e32 v221, 7, v153
	v_and_b32_e32 v222, 7, v220
	v_xor_b32_e32 v222, v222, v221
	v_lshlrev_b32_e32 v222, 4, v222
	v_lshl_add_u32 v114, v220, 7, v222
	v_mul_u32_u24_e32 v123, 0x90, v220
	v_lshl_add_u32 v123, v221, 4, v123
	v_add_u32_e32 v123, 0x2400, v123
	v_mul_u32_u24_e32 v117, 0x600, v220
	v_lshl_add_u32 v117, v221, 4, v117
	v_lshlrev_b32_e32 v118, 12, v220
	v_lshl_add_u32 v118, v221, 4, v118
	v_mul_u32_u24_e32 v116, 0x90, v112
	v_lshl_add_u32 v116, v113, 3, v116
	v_and_b32_e32 v222, 7, v112
	v_xor_b32_e32 v222, v222, v113
	v_lshlrev_b32_e32 v222, 4, v222
	v_lshl_add_u32 v115, v112, 7, v222
	v_xor_b32_e32 v122, 64, v115
	s_lshl_b32 s1, s0, 13
	s_add_i32 s1, s1, 0x9000
	v_lshl_add_u32 v250, v152, 4, s1
	v_mov_b32_e32 v226, 0xf149f2ca
	v_mov_b32_e32 v227, 0xff61b1e6
	v_mov_b32_e32 v203, 0x41000000
	v_mov_b32_e32 v238, 0
	v_mov_b32_e32 v224, 0xff800000
	s_cmp_lt_u32 s0, 4
	s_cbranch_scc0 .Lnsa_prio
	s_setprio 1
